# G1 epilogue v3: additional DPP row_ror:8 exchange so each dwordx4 store writes 8 full 128-byte rows
# speedup vs baseline: 1.1848x; 1.0020x over previous
; __device__ __forceinline__ void gemm_core_big(const bf16_t* __restrict__ A, int lda, const bf16_t* __restrict__ Bt, int ldb,
;                                               int K, f32x4 (&acc)[8][4], char* smem) {
;     ...
;   u32x4 ra[8], rb[4];
; #pragma unroll
;   for (int i = 0; i < 8; ++i) ra[i] = *(const u32x4*)(ap + (size_t)(32 * i) * lda);
; #pragma unroll
;   for (int i = 0; i < 4; ++i) rb[i] = *(const u32x4*)(bp + (size_t)(32 * i) * ldb);
;   for (int kt = 0; kt < nk; ++kt) {
;     __syncthreads();
; #pragma unroll
;     for (int i = 0; i < 8; ++i) *(u32x4*)(wA + 32 * i * LDS_STRIDE) = ra[i];
; #pragma unroll
;     for (int i = 0; i < 4; ++i) *(u32x4*)(wB + 32 * i * LDS_STRIDE) = rb[i];
;     __syncthreads();
;     {
;       const int k1 = min(kt + 1, nk - 1) << 6;
; #pragma unroll
;       for (int i = 0; i < 8; ++i) ra[i] = *(const u32x4*)(ap + (size_t)(32 * i) * lda + k1);
; #pragma unroll
;       for (int i = 0; i < 4; ++i) rb[i] = *(const u32x4*)(bp + (size_t)(32 * i) * ldb + k1);
;     }
; #pragma unroll
;     for (int ks = 0; ks < 2; ++ks) {
;       const int fo = ks ? fo1 : fo0;
;       bf16x8 bfr[4];
; #pragma unroll
;       for (int j = 0; j < 4; ++j) bfr[j] = *(const bf16x8*)(cB + j * 16 * LDS_STRIDE + fo);
; #pragma unroll
;       for (int i = 0; i < 8; ++i) {
;         const bf16x8 af = *(const bf16x8*)(cA + i * 16 * LDS_STRIDE + fo);
; #pragma unroll
;         for (int j = 0; j < 4; ++j)
;           acc[i][j] = __builtin_amdgcn_mfma_f32_16x16x32_bf16(bfr[j], af, acc[i][j], 0, 0, 0);
;       }
;     }
;   }
.LBB0_711:
	s_setprio 0
	global_load_dwordx4 v[144:147], v224, s[30:31]
	global_load_dwordx4 v[148:151], v224, s[28:29]
	global_load_dwordx4 v[134:137], v225, s[28:29]
	global_load_dwordx4 v[152:155], v226, s[28:29]
	global_load_dwordx4 v[156:159], v227, s[28:29]
	global_load_dwordx4 v[160:163], v228, s[28:29]
	global_load_dwordx4 v[164:167], v229, s[28:29]
	global_load_dwordx4 v[168:171], v230, s[28:29]
	global_load_dwordx4 v[172:175], v231, s[28:29]
	global_load_dwordx4 v[188:191], v225, s[30:31]
	global_load_dwordx4 v[192:195], v226, s[30:31]
	global_load_dwordx4 v[196:199], v227, s[30:31]
	s_add_u32 s28, s28, 0x80
	s_addc_u32 s29, s29, 0
	s_add_u32 s30, s30, 0x80
	s_addc_u32 s31, s31, 0
	s_barrier
	s_add_i32 s26, s26, 1
	s_lshl_b32 s18, s13, 7
	s_cmp_lg_u32 s26, 17
	s_waitcnt vmcnt(10)
	ds_write_b128 v2, v[148:151]
	ds_write_b128 v2, v[144:147] offset:32768
	s_waitcnt vmcnt(9)
	ds_write_b128 v2, v[134:137] offset:4096
	s_waitcnt vmcnt(8)
	ds_write_b128 v2, v[152:155] offset:8192
	s_waitcnt vmcnt(7)
	ds_write_b128 v2, v[156:159] offset:12288
	s_waitcnt vmcnt(6)
	ds_write_b128 v2, v[160:163] offset:16384
	s_waitcnt vmcnt(5)
	ds_write_b128 v2, v[164:167] offset:20480
	s_waitcnt vmcnt(4)
	ds_write_b128 v2, v[168:171] offset:24576
	s_waitcnt vmcnt(3)
	ds_write_b128 v2, v[172:175] offset:28672
	s_waitcnt vmcnt(2)
	ds_write_b128 v2, v[188:191] offset:36864
	s_waitcnt vmcnt(1)
	ds_write_b128 v2, v[192:195] offset:40960
	s_waitcnt vmcnt(0)
	ds_write_b128 v2, v[196:199] offset:45056
	s_waitcnt lgkmcnt(0)
	s_barrier
	ds_read_b128 v[134:137], v140 offset:32768
	ds_read_b128 v[144:147], v140 offset:34816
	ds_read_b128 v[156:159], v140 offset:36864
	ds_read_b128 v[160:163], v140 offset:38912
	ds_read_b128 v[148:151], v141 offset:0
	ds_read_b128 v[152:155], v141 offset:2048
	ds_read_b128 v[216:219], v141 offset:4096
	ds_read_b128 v[220:223], v141 offset:6144
	s_setprio 1
	s_waitcnt lgkmcnt(3)
	v_mfma_f32_16x16x32_bf16 v[128:131], v[134:137], v[148:151], v[128:131]
	v_mfma_f32_16x16x32_bf16 v[124:127], v[144:147], v[148:151], v[124:127]
	v_mfma_f32_16x16x32_bf16 v[120:123], v[156:159], v[148:151], v[120:123]
	v_mfma_f32_16x16x32_bf16 v[116:119], v[160:163], v[148:151], v[116:119]
	s_waitcnt lgkmcnt(2)
	v_mfma_f32_16x16x32_bf16 v[112:115], v[134:137], v[152:155], v[112:115]
	v_mfma_f32_16x16x32_bf16 v[108:111], v[144:147], v[152:155], v[108:111]
	v_mfma_f32_16x16x32_bf16 v[104:107], v[156:159], v[152:155], v[104:107]
	v_mfma_f32_16x16x32_bf16 v[100:103], v[160:163], v[152:155], v[100:103]
	ds_read_b128 v[148:151], v141 offset:8192
	ds_read_b128 v[152:155], v141 offset:10240
	s_waitcnt lgkmcnt(3)
	v_mfma_f32_16x16x32_bf16 v[96:99], v[134:137], v[216:219], v[96:99]
	v_mfma_f32_16x16x32_bf16 v[92:95], v[144:147], v[216:219], v[92:95]
	v_mfma_f32_16x16x32_bf16 v[88:91], v[156:159], v[216:219], v[88:91]
	v_mfma_f32_16x16x32_bf16 v[84:87], v[160:163], v[216:219], v[84:87]
	s_waitcnt lgkmcnt(2)
	v_mfma_f32_16x16x32_bf16 v[80:83], v[134:137], v[220:223], v[80:83]
	v_mfma_f32_16x16x32_bf16 v[76:79], v[144:147], v[220:223], v[76:79]
	v_mfma_f32_16x16x32_bf16 v[72:75], v[156:159], v[220:223], v[72:75]
	v_mfma_f32_16x16x32_bf16 v[68:71], v[160:163], v[220:223], v[68:71]
	ds_read_b128 v[216:219], v141 offset:12288
	ds_read_b128 v[220:223], v141 offset:14336
	ds_read_b128 v[200:203], v142 offset:32768
	ds_read_b128 v[204:207], v142 offset:34816
	ds_read_b128 v[208:211], v142 offset:36864
	ds_read_b128 v[212:215], v142 offset:38912
	s_waitcnt lgkmcnt(7)
	v_mfma_f32_16x16x32_bf16 v[64:67], v[134:137], v[148:151], v[64:67]
	v_mfma_f32_16x16x32_bf16 v[60:63], v[144:147], v[148:151], v[60:63]
	v_mfma_f32_16x16x32_bf16 v[56:59], v[156:159], v[148:151], v[56:59]
	v_mfma_f32_16x16x32_bf16 v[52:55], v[160:163], v[148:151], v[52:55]
	s_waitcnt lgkmcnt(6)
	v_mfma_f32_16x16x32_bf16 v[48:51], v[134:137], v[152:155], v[48:51]
	v_mfma_f32_16x16x32_bf16 v[44:47], v[144:147], v[152:155], v[44:47]
	v_mfma_f32_16x16x32_bf16 v[40:43], v[156:159], v[152:155], v[40:43]
	v_mfma_f32_16x16x32_bf16 v[36:39], v[160:163], v[152:155], v[36:39]
	ds_read_b128 v[148:151], v143 offset:0
	ds_read_b128 v[152:155], v143 offset:2048
	s_waitcnt lgkmcnt(7)
	v_mfma_f32_16x16x32_bf16 v[32:35], v[134:137], v[216:219], v[32:35]
	v_mfma_f32_16x16x32_bf16 v[24:27], v[144:147], v[216:219], v[24:27]
	v_mfma_f32_16x16x32_bf16 v[20:23], v[156:159], v[216:219], v[20:23]
	v_mfma_f32_16x16x32_bf16 v[16:19], v[160:163], v[216:219], v[16:19]
	s_waitcnt lgkmcnt(6)
	v_mfma_f32_16x16x32_bf16 v[12:15], v[134:137], v[220:223], v[12:15]
	v_mfma_f32_16x16x32_bf16 v[8:11], v[144:147], v[220:223], v[8:11]
	v_mfma_f32_16x16x32_bf16 v[4:7], v[156:159], v[220:223], v[4:7]
	v_mfma_f32_16x16x32_bf16 v[28:31], v[160:163], v[220:223], v[28:31]
	ds_read_b128 v[216:219], v143 offset:4096
	ds_read_b128 v[220:223], v143 offset:6144
	s_waitcnt lgkmcnt(3)
	v_mfma_f32_16x16x32_bf16 v[128:131], v[200:203], v[148:151], v[128:131]
	v_mfma_f32_16x16x32_bf16 v[124:127], v[204:207], v[148:151], v[124:127]
	v_mfma_f32_16x16x32_bf16 v[120:123], v[208:211], v[148:151], v[120:123]
	v_mfma_f32_16x16x32_bf16 v[116:119], v[212:215], v[148:151], v[116:119]
	s_waitcnt lgkmcnt(2)
	v_mfma_f32_16x16x32_bf16 v[112:115], v[200:203], v[152:155], v[112:115]
	v_mfma_f32_16x16x32_bf16 v[108:111], v[204:207], v[152:155], v[108:111]
	v_mfma_f32_16x16x32_bf16 v[104:107], v[208:211], v[152:155], v[104:107]
	v_mfma_f32_16x16x32_bf16 v[100:103], v[212:215], v[152:155], v[100:103]
	ds_read_b128 v[148:151], v143 offset:8192
	ds_read_b128 v[152:155], v143 offset:10240
	s_waitcnt lgkmcnt(3)
; __device__ __forceinline__ unsigned pack2(float a, float b) { return (unsigned)f2bf(a) | ((unsigned)f2bf(b) << 16); }
; __device__ __forceinline__ void gemm_core_big(const bf16_t* __restrict__ A, int lda, const bf16_t* __restrict__ Bt, int ldb,
;                                               int K, f32x4 (&acc)[8][4], char* smem) {
;     ...
;     for (int ks = 0; ks < 2; ++ks) {
;       const int fo = ks ? fo1 : fo0;
;       bf16x8 bfr[4];
; #pragma unroll
;       for (int j = 0; j < 4; ++j) bfr[j] = *(const bf16x8*)(cB + j * 16 * LDS_STRIDE + fo);
; #pragma unroll
;       for (int i = 0; i < 8; ++i) {
;         const bf16x8 af = *(const bf16x8*)(cA + i * 16 * LDS_STRIDE + fo);
; #pragma unroll
;         for (int j = 0; j < 4; ++j)
;           acc[i][j] = __builtin_amdgcn_mfma_f32_16x16x32_bf16(bfr[j], af, acc[i][j], 0, 0, 0);
;       }
;     }
; __device__ __forceinline__ void phase_gemm_in(const Params& p, char* smem) {
;     ...
;     bf16_t* dst; int ldd, ncol0;
;     if (nt < PRE_W / 128) { dst = PRE; ldd = PRE_W; ncol0 = nt * 128; }
;     else { dst = POST; ldd = POST_W; ncol0 = (nt - PRE_W / 128) * 128; }
; #pragma unroll
;     for (int i = 0; i < 8; ++i) {
;       const int m = mt * 256 + wm * 128 + i * 16 + (lane & 15);
; #pragma unroll
;       for (int j = 0; j < 4; ++j) {
;         const int n = ncol0 + wn * 64 + j * 16 + (lane >> 4) * 4;
;         uint2 o;
;         o.x = pack2(acc[i][j][0], acc[i][j][1]);
;         o.y = pack2(acc[i][j][2], acc[i][j][3]);
;         *(uint2*)(dst + (size_t)m * ldd + n) = o;
;       }
;     }
	v_mfma_f32_16x16x32_bf16 v[96:99], v[200:203], v[216:219], v[96:99]
	v_mfma_f32_16x16x32_bf16 v[92:95], v[204:207], v[216:219], v[92:95]
	v_mfma_f32_16x16x32_bf16 v[88:91], v[208:211], v[216:219], v[88:91]
	v_mfma_f32_16x16x32_bf16 v[84:87], v[212:215], v[216:219], v[84:87]
	s_waitcnt lgkmcnt(2)
	v_mfma_f32_16x16x32_bf16 v[80:83], v[200:203], v[220:223], v[80:83]
	v_mfma_f32_16x16x32_bf16 v[76:79], v[204:207], v[220:223], v[76:79]
	v_mfma_f32_16x16x32_bf16 v[72:75], v[208:211], v[220:223], v[72:75]
	v_mfma_f32_16x16x32_bf16 v[68:71], v[212:215], v[220:223], v[68:71]
	ds_read_b128 v[216:219], v143 offset:12288
	ds_read_b128 v[220:223], v143 offset:14336
	s_waitcnt lgkmcnt(3)
	v_mfma_f32_16x16x32_bf16 v[64:67], v[200:203], v[148:151], v[64:67]
	v_mfma_f32_16x16x32_bf16 v[60:63], v[204:207], v[148:151], v[60:63]
	v_mfma_f32_16x16x32_bf16 v[56:59], v[208:211], v[148:151], v[56:59]
	v_mfma_f32_16x16x32_bf16 v[52:55], v[212:215], v[148:151], v[52:55]
	s_waitcnt lgkmcnt(2)
	v_mfma_f32_16x16x32_bf16 v[48:51], v[200:203], v[152:155], v[48:51]
	v_mfma_f32_16x16x32_bf16 v[44:47], v[204:207], v[152:155], v[44:47]
	v_mfma_f32_16x16x32_bf16 v[40:43], v[208:211], v[152:155], v[40:43]
	v_mfma_f32_16x16x32_bf16 v[36:39], v[212:215], v[152:155], v[36:39]
	s_waitcnt lgkmcnt(1)
	v_mfma_f32_16x16x32_bf16 v[32:35], v[200:203], v[216:219], v[32:35]
	v_mfma_f32_16x16x32_bf16 v[24:27], v[204:207], v[216:219], v[24:27]
	v_mfma_f32_16x16x32_bf16 v[20:23], v[208:211], v[216:219], v[20:23]
	v_mfma_f32_16x16x32_bf16 v[16:19], v[212:215], v[216:219], v[16:19]
	s_waitcnt lgkmcnt(0)
	v_mfma_f32_16x16x32_bf16 v[12:15], v[200:203], v[220:223], v[12:15]
	v_mfma_f32_16x16x32_bf16 v[8:11], v[204:207], v[220:223], v[8:11]
	v_mfma_f32_16x16x32_bf16 v[4:7], v[208:211], v[220:223], v[4:7]
	v_mfma_f32_16x16x32_bf16 v[28:31], v[212:215], v[220:223], v[28:31]
	s_cbranch_scc1 .LBB0_711
	s_setprio 0
	s_lshl_b32 s13, s14, 7
	s_add_i32 s15, s13, 0xffffef00
	s_cmp_lt_i32 s14, 34
	s_mov_b32 s14, 0x4100000
	s_cselect_b32 s18, s14, 0xcb20000
	s_movk_i32 s0, 0x1200
	s_cselect_b32 s15, s13, s15
	s_cselect_b32 s14, 0x1100, s0
	v_lshl_add_u32 v2, s12, 8, v138
	s_add_u32 s12, s10, s18
	v_or_b32_e32 v0, s15, v139
	s_addc_u32 s13, s11, 0
	s_lshl_b32 s18, s14, 4
	v_ashrrev_i32_e32 v1, 31, v0
	v_lshlrev_b64 v[0:1], 1, v[0:1]
	v_bfe_u32 v136, v178, 4, 1
	v_mul_u32_u24_e32 v136, 24, v136
	v_add_u32_e32 v0, v0, v136
	v_bfe_u32 v136, v178, 3, 1
	v_lshlrev_b32_e32 v136, 6, v136
	v_add_u32_e32 v0, v0, v136
	v_and_b32_e32 v2, 0xfffffff7, v2
	v_mad_i64_i32 v[132:133], s[26:27], s14, v2, 0
	v_lshl_add_u64 v[132:133], v[132:133], 1, s[12:13]
	v_lshl_add_u64 v[132:133], v[132:133], 0, v[0:1]
	v_lshl_add_u64 v[134:135], v[132:133], 0, s[18:19]
	v_cvt_pk_bf16_f32 v144, v128, v129
	v_cvt_pk_bf16_f32 v146, v124, v125
	v_cvt_pk_bf16_f32 v145, v130, v131
	v_cvt_pk_bf16_f32 v147, v126, v127
	v_cvt_pk_bf16_f32 v148, v120, v121
	v_cvt_pk_bf16_f32 v150, v116, v117
	v_cvt_pk_bf16_f32 v149, v122, v123
	v_cvt_pk_bf16_f32 v151, v118, v119
	v_permlane16_swap_b32_e32 v144, v146
	v_permlane16_swap_b32_e32 v145, v147
	v_permlane16_swap_b32_e32 v148, v150
	v_permlane16_swap_b32_e32 v149, v151
	v_mov_b32_e32 v152, v144
	v_mov_b32_e32 v153, v145
	v_mov_b32_e32 v154, v146
	v_mov_b32_e32 v155, v147
	v_mov_b32_dpp v144, v148 row_ror:8 row_mask:0xf bank_mask:0xc
	v_mov_b32_dpp v145, v149 row_ror:8 row_mask:0xf bank_mask:0xc
	v_mov_b32_dpp v146, v150 row_ror:8 row_mask:0xf bank_mask:0xc
	v_mov_b32_dpp v147, v151 row_ror:8 row_mask:0xf bank_mask:0xc
	v_mov_b32_dpp v148, v152 row_ror:8 row_mask:0xf bank_mask:0x3
	v_mov_b32_dpp v149, v153 row_ror:8 row_mask:0xf bank_mask:0x3
	v_mov_b32_dpp v150, v154 row_ror:8 row_mask:0xf bank_mask:0x3
	v_mov_b32_dpp v151, v155 row_ror:8 row_mask:0xf bank_mask:0x3
	global_store_dwordx4 v[132:133], v[144:147], off
	global_store_dwordx4 v[134:135], v[148:151], off
	v_or_b32_e32 v172, 0x10, v2
	v_mad_i64_i32 v[168:169], s[26:27], s14, v172, 0
	v_lshl_add_u64 v[168:169], v[168:169], 1, s[12:13]
	v_lshl_add_u64 v[168:169], v[168:169], 0, v[0:1]
	v_lshl_add_u64 v[170:171], v[168:169], 0, s[18:19]
	v_cvt_pk_bf16_f32 v156, v112, v113
	v_cvt_pk_bf16_f32 v158, v108, v109
	v_cvt_pk_bf16_f32 v157, v114, v115
	v_cvt_pk_bf16_f32 v159, v110, v111
	v_cvt_pk_bf16_f32 v160, v104, v105
	v_cvt_pk_bf16_f32 v162, v100, v101
	v_cvt_pk_bf16_f32 v161, v106, v107
	v_cvt_pk_bf16_f32 v163, v102, v103
	v_permlane16_swap_b32_e32 v156, v158
	v_permlane16_swap_b32_e32 v157, v159
	v_permlane16_swap_b32_e32 v160, v162
	v_permlane16_swap_b32_e32 v161, v163
	v_mov_b32_e32 v164, v156
	v_mov_b32_e32 v165, v157
	v_mov_b32_e32 v166, v158
	v_mov_b32_e32 v167, v159
	v_mov_b32_dpp v156, v160 row_ror:8 row_mask:0xf bank_mask:0xc
	v_mov_b32_dpp v157, v161 row_ror:8 row_mask:0xf bank_mask:0xc
	v_mov_b32_dpp v158, v162 row_ror:8 row_mask:0xf bank_mask:0xc
	v_mov_b32_dpp v159, v163 row_ror:8 row_mask:0xf bank_mask:0xc
	v_mov_b32_dpp v160, v164 row_ror:8 row_mask:0xf bank_mask:0x3
	v_mov_b32_dpp v161, v165 row_ror:8 row_mask:0xf bank_mask:0x3
	v_mov_b32_dpp v162, v166 row_ror:8 row_mask:0xf bank_mask:0x3
	v_mov_b32_dpp v163, v167 row_ror:8 row_mask:0xf bank_mask:0x3
	global_store_dwordx4 v[168:169], v[156:159], off
	global_store_dwordx4 v[170:171], v[160:163], off
	v_or_b32_e32 v172, 0x20, v2
	v_mad_i64_i32 v[132:133], s[26:27], s14, v172, 0
	v_lshl_add_u64 v[132:133], v[132:133], 1, s[12:13]
	v_lshl_add_u64 v[132:133], v[132:133], 0, v[0:1]
	v_lshl_add_u64 v[134:135], v[132:133], 0, s[18:19]
	v_cvt_pk_bf16_f32 v144, v96, v97
	v_cvt_pk_bf16_f32 v146, v92, v93
	v_cvt_pk_bf16_f32 v145, v98, v99
	v_cvt_pk_bf16_f32 v147, v94, v95
	v_cvt_pk_bf16_f32 v148, v88, v89
; __device__ __forceinline__ unsigned pack2(float a, float b) { return (unsigned)f2bf(a) | ((unsigned)f2bf(b) << 16); }
; __device__ __forceinline__ void phase_gemm_in(const Params& p, char* smem) {
;     ...
; #pragma unroll
;     for (int i = 0; i < 8; ++i) {
;       const int m = mt * 256 + wm * 128 + i * 16 + (lane & 15);
; #pragma unroll
;       for (int j = 0; j < 4; ++j) {
;         const int n = ncol0 + wn * 64 + j * 16 + (lane >> 4) * 4;
;         uint2 o;
;         o.x = pack2(acc[i][j][0], acc[i][j][1]);
;         o.y = pack2(acc[i][j][2], acc[i][j][3]);
;         *(uint2*)(dst + (size_t)m * ldd + n) = o;
;       }
;     }
	v_cvt_pk_bf16_f32 v150, v84, v85
	v_cvt_pk_bf16_f32 v149, v90, v91
	v_cvt_pk_bf16_f32 v151, v86, v87
	v_permlane16_swap_b32_e32 v144, v146
	v_permlane16_swap_b32_e32 v145, v147
	v_permlane16_swap_b32_e32 v148, v150
	v_permlane16_swap_b32_e32 v149, v151
	v_mov_b32_e32 v152, v144
	v_mov_b32_e32 v153, v145
	v_mov_b32_e32 v154, v146
	v_mov_b32_e32 v155, v147
	v_mov_b32_dpp v144, v148 row_ror:8 row_mask:0xf bank_mask:0xc
	v_mov_b32_dpp v145, v149 row_ror:8 row_mask:0xf bank_mask:0xc
	v_mov_b32_dpp v146, v150 row_ror:8 row_mask:0xf bank_mask:0xc
	v_mov_b32_dpp v147, v151 row_ror:8 row_mask:0xf bank_mask:0xc
	v_mov_b32_dpp v148, v152 row_ror:8 row_mask:0xf bank_mask:0x3
	v_mov_b32_dpp v149, v153 row_ror:8 row_mask:0xf bank_mask:0x3
	v_mov_b32_dpp v150, v154 row_ror:8 row_mask:0xf bank_mask:0x3
	v_mov_b32_dpp v151, v155 row_ror:8 row_mask:0xf bank_mask:0x3
	global_store_dwordx4 v[132:133], v[144:147], off
	global_store_dwordx4 v[134:135], v[148:151], off
	v_or_b32_e32 v172, 0x30, v2
	v_mad_i64_i32 v[168:169], s[26:27], s14, v172, 0
	v_lshl_add_u64 v[168:169], v[168:169], 1, s[12:13]
	v_lshl_add_u64 v[168:169], v[168:169], 0, v[0:1]
	v_lshl_add_u64 v[170:171], v[168:169], 0, s[18:19]
	v_cvt_pk_bf16_f32 v156, v80, v81
	v_cvt_pk_bf16_f32 v158, v76, v77
	v_cvt_pk_bf16_f32 v157, v82, v83
	v_cvt_pk_bf16_f32 v159, v78, v79
	v_cvt_pk_bf16_f32 v160, v72, v73
	v_cvt_pk_bf16_f32 v162, v68, v69
	v_cvt_pk_bf16_f32 v161, v74, v75
	v_cvt_pk_bf16_f32 v163, v70, v71
	v_permlane16_swap_b32_e32 v156, v158
	v_permlane16_swap_b32_e32 v157, v159
	v_permlane16_swap_b32_e32 v160, v162
	v_permlane16_swap_b32_e32 v161, v163
	v_mov_b32_e32 v164, v156
	v_mov_b32_e32 v165, v157
	v_mov_b32_e32 v166, v158
	v_mov_b32_e32 v167, v159
	v_mov_b32_dpp v156, v160 row_ror:8 row_mask:0xf bank_mask:0xc
	v_mov_b32_dpp v157, v161 row_ror:8 row_mask:0xf bank_mask:0xc
	v_mov_b32_dpp v158, v162 row_ror:8 row_mask:0xf bank_mask:0xc
	v_mov_b32_dpp v159, v163 row_ror:8 row_mask:0xf bank_mask:0xc
	v_mov_b32_dpp v160, v164 row_ror:8 row_mask:0xf bank_mask:0x3
	v_mov_b32_dpp v161, v165 row_ror:8 row_mask:0xf bank_mask:0x3
	v_mov_b32_dpp v162, v166 row_ror:8 row_mask:0xf bank_mask:0x3
	v_mov_b32_dpp v163, v167 row_ror:8 row_mask:0xf bank_mask:0x3
	global_store_dwordx4 v[168:169], v[156:159], off
	global_store_dwordx4 v[170:171], v[160:163], off
	v_or_b32_e32 v172, 0x40, v2
	v_mad_i64_i32 v[132:133], s[26:27], s14, v172, 0
	v_lshl_add_u64 v[132:133], v[132:133], 1, s[12:13]
	v_lshl_add_u64 v[132:133], v[132:133], 0, v[0:1]
	v_lshl_add_u64 v[134:135], v[132:133], 0, s[18:19]
	v_cvt_pk_bf16_f32 v144, v64, v65
	v_cvt_pk_bf16_f32 v146, v60, v61
	v_cvt_pk_bf16_f32 v145, v66, v67
	v_cvt_pk_bf16_f32 v147, v62, v63
	v_cvt_pk_bf16_f32 v148, v56, v57
	v_cvt_pk_bf16_f32 v150, v52, v53
	v_cvt_pk_bf16_f32 v149, v58, v59
	v_cvt_pk_bf16_f32 v151, v54, v55
	v_permlane16_swap_b32_e32 v144, v146
	v_permlane16_swap_b32_e32 v145, v147
	v_permlane16_swap_b32_e32 v148, v150
	v_permlane16_swap_b32_e32 v149, v151
	v_mov_b32_e32 v152, v144
	v_mov_b32_e32 v153, v145
	v_mov_b32_e32 v154, v146
	v_mov_b32_e32 v155, v147
	v_mov_b32_dpp v144, v148 row_ror:8 row_mask:0xf bank_mask:0xc
	v_mov_b32_dpp v145, v149 row_ror:8 row_mask:0xf bank_mask:0xc
	v_mov_b32_dpp v146, v150 row_ror:8 row_mask:0xf bank_mask:0xc
	v_mov_b32_dpp v147, v151 row_ror:8 row_mask:0xf bank_mask:0xc
	v_mov_b32_dpp v148, v152 row_ror:8 row_mask:0xf bank_mask:0x3
	v_mov_b32_dpp v149, v153 row_ror:8 row_mask:0xf bank_mask:0x3
	v_mov_b32_dpp v150, v154 row_ror:8 row_mask:0xf bank_mask:0x3
	v_mov_b32_dpp v151, v155 row_ror:8 row_mask:0xf bank_mask:0x3
	global_store_dwordx4 v[132:133], v[144:147], off
	global_store_dwordx4 v[134:135], v[148:151], off
	v_or_b32_e32 v172, 0x50, v2
	v_mad_i64_i32 v[168:169], s[26:27], s14, v172, 0
	v_lshl_add_u64 v[168:169], v[168:169], 1, s[12:13]
	v_lshl_add_u64 v[168:169], v[168:169], 0, v[0:1]
	v_lshl_add_u64 v[170:171], v[168:169], 0, s[18:19]
	v_cvt_pk_bf16_f32 v156, v48, v49
; __device__ __forceinline__ unsigned pack2(float a, float b) { return (unsigned)f2bf(a) | ((unsigned)f2bf(b) << 16); }
; __device__ __forceinline__ void phase_gemm_in(const Params& p, char* smem) {
;     ...
; #pragma unroll
;     for (int i = 0; i < 8; ++i) {
;       const int m = mt * 256 + wm * 128 + i * 16 + (lane & 15);
; #pragma unroll
;       for (int j = 0; j < 4; ++j) {
;         const int n = ncol0 + wn * 64 + j * 16 + (lane >> 4) * 4;
;         uint2 o;
;         o.x = pack2(acc[i][j][0], acc[i][j][1]);
;         o.y = pack2(acc[i][j][2], acc[i][j][3]);
;         *(uint2*)(dst + (size_t)m * ldd + n) = o;
;       }
;     }
	v_cvt_pk_bf16_f32 v158, v44, v45
	v_cvt_pk_bf16_f32 v157, v50, v51
	v_cvt_pk_bf16_f32 v159, v46, v47
	v_cvt_pk_bf16_f32 v160, v40, v41
	v_cvt_pk_bf16_f32 v162, v36, v37
	v_cvt_pk_bf16_f32 v161, v42, v43
	v_cvt_pk_bf16_f32 v163, v38, v39
	v_permlane16_swap_b32_e32 v156, v158
	v_permlane16_swap_b32_e32 v157, v159
	v_permlane16_swap_b32_e32 v160, v162
	v_permlane16_swap_b32_e32 v161, v163
	v_mov_b32_e32 v164, v156
	v_mov_b32_e32 v165, v157
	v_mov_b32_e32 v166, v158
	v_mov_b32_e32 v167, v159
	v_mov_b32_dpp v156, v160 row_ror:8 row_mask:0xf bank_mask:0xc
	v_mov_b32_dpp v157, v161 row_ror:8 row_mask:0xf bank_mask:0xc
	v_mov_b32_dpp v158, v162 row_ror:8 row_mask:0xf bank_mask:0xc
	v_mov_b32_dpp v159, v163 row_ror:8 row_mask:0xf bank_mask:0xc
	v_mov_b32_dpp v160, v164 row_ror:8 row_mask:0xf bank_mask:0x3
	v_mov_b32_dpp v161, v165 row_ror:8 row_mask:0xf bank_mask:0x3
	v_mov_b32_dpp v162, v166 row_ror:8 row_mask:0xf bank_mask:0x3
	v_mov_b32_dpp v163, v167 row_ror:8 row_mask:0xf bank_mask:0x3
	global_store_dwordx4 v[168:169], v[156:159], off
	global_store_dwordx4 v[170:171], v[160:163], off
	v_or_b32_e32 v172, 0x60, v2
	v_mad_i64_i32 v[132:133], s[26:27], s14, v172, 0
	v_lshl_add_u64 v[132:133], v[132:133], 1, s[12:13]
	v_lshl_add_u64 v[132:133], v[132:133], 0, v[0:1]
	v_lshl_add_u64 v[134:135], v[132:133], 0, s[18:19]
	v_cvt_pk_bf16_f32 v144, v32, v33
	v_cvt_pk_bf16_f32 v146, v24, v25
	v_cvt_pk_bf16_f32 v145, v34, v35
	v_cvt_pk_bf16_f32 v147, v26, v27
	v_cvt_pk_bf16_f32 v148, v20, v21
	v_cvt_pk_bf16_f32 v150, v16, v17
	v_cvt_pk_bf16_f32 v149, v22, v23
	v_cvt_pk_bf16_f32 v151, v18, v19
	v_permlane16_swap_b32_e32 v144, v146
	v_permlane16_swap_b32_e32 v145, v147
	v_permlane16_swap_b32_e32 v148, v150
	v_permlane16_swap_b32_e32 v149, v151
	v_mov_b32_e32 v152, v144
	v_mov_b32_e32 v153, v145
	v_mov_b32_e32 v154, v146
	v_mov_b32_e32 v155, v147
	v_mov_b32_dpp v144, v148 row_ror:8 row_mask:0xf bank_mask:0xc
	v_mov_b32_dpp v145, v149 row_ror:8 row_mask:0xf bank_mask:0xc
	v_mov_b32_dpp v146, v150 row_ror:8 row_mask:0xf bank_mask:0xc
	v_mov_b32_dpp v147, v151 row_ror:8 row_mask:0xf bank_mask:0xc
	v_mov_b32_dpp v148, v152 row_ror:8 row_mask:0xf bank_mask:0x3
	v_mov_b32_dpp v149, v153 row_ror:8 row_mask:0xf bank_mask:0x3
	v_mov_b32_dpp v150, v154 row_ror:8 row_mask:0xf bank_mask:0x3
	v_mov_b32_dpp v151, v155 row_ror:8 row_mask:0xf bank_mask:0x3
	global_store_dwordx4 v[132:133], v[144:147], off
	global_store_dwordx4 v[134:135], v[148:151], off
	v_or_b32_e32 v172, 0x70, v2
	v_mad_i64_i32 v[168:169], s[26:27], s14, v172, 0
	v_lshl_add_u64 v[168:169], v[168:169], 1, s[12:13]
	v_lshl_add_u64 v[168:169], v[168:169], 0, v[0:1]
	v_lshl_add_u64 v[170:171], v[168:169], 0, s[18:19]
	v_cvt_pk_bf16_f32 v156, v12, v13
	v_cvt_pk_bf16_f32 v158, v8, v9
	v_cvt_pk_bf16_f32 v157, v14, v15
	v_cvt_pk_bf16_f32 v159, v10, v11
	v_cvt_pk_bf16_f32 v160, v4, v5
	v_cvt_pk_bf16_f32 v162, v28, v29
	v_cvt_pk_bf16_f32 v161, v6, v7
	v_cvt_pk_bf16_f32 v163, v30, v31
	v_permlane16_swap_b32_e32 v156, v158
	v_permlane16_swap_b32_e32 v157, v159
	v_permlane16_swap_b32_e32 v160, v162
	v_permlane16_swap_b32_e32 v161, v163
	v_mov_b32_e32 v164, v156
	v_mov_b32_e32 v165, v157
	v_mov_b32_e32 v166, v158
	v_mov_b32_e32 v167, v159
	v_mov_b32_dpp v156, v160 row_ror:8 row_mask:0xf bank_mask:0xc
	v_mov_b32_dpp v157, v161 row_ror:8 row_mask:0xf bank_mask:0xc
	v_mov_b32_dpp v158, v162 row_ror:8 row_mask:0xf bank_mask:0xc
	v_mov_b32_dpp v159, v163 row_ror:8 row_mask:0xf bank_mask:0xc
	v_mov_b32_dpp v160, v164 row_ror:8 row_mask:0xf bank_mask:0x3
	v_mov_b32_dpp v161, v165 row_ror:8 row_mask:0xf bank_mask:0x3
	v_mov_b32_dpp v162, v166 row_ror:8 row_mask:0xf bank_mask:0x3
	v_mov_b32_dpp v163, v167 row_ror:8 row_mask:0xf bank_mask:0x3
	global_store_dwordx4 v[168:169], v[156:159], off
	global_store_dwordx4 v[170:171], v[160:163], off
	s_add_i32 s23, s23, 1
	s_cmp_eq_u32 s23, s17
	s_cselect_b64 s[12:13], -1, 0
	s_mov_b32 s31, 0x18000
	s_branch .LBB0_708
